# P3->G2 barrier split added on top: arrive after the SSM part, wait after the chunk mixer
# speedup vs baseline: 1.0128x; 1.0034x over previous
.Lssm_done:
	s_waitcnt vmcnt(0) lgkmcnt(0)
	s_barrier
	s_mov_b64 s[4:5], exec
	v_readlane_b32 s6, v254, 2
	v_readlane_b32 s7, v254, 3
	s_nop 1
	s_and_b64 s[6:7], s[4:5], s[6:7]
	s_mov_b64 exec, s[6:7]
	s_cbranch_execz .Lp3_arrive_join
	s_getreg_b32 s10, hwreg(HW_REG_XCC_ID, 0, 4)
	v_mov_b32_e32 v2, 0x23fc0
	ds_read_b64 v[2:3], v2
	s_lshl_b32 s10, s10, 6
	s_add_u32 s12, s62, 0x40e000
	s_addc_u32 s13, s63, 0
	v_mov_b32_e32 v4, s10
	v_mov_b32_e32 v5, 1
	global_atomic_add v6, v4, v5, s[12:13] sc0
	s_waitcnt vmcnt(0) lgkmcnt(0)
	v_add_u32_e32 v6, 1, v6
	v_cmp_eq_u32_e32 vcc, v6, v2
	s_cbranch_vccz .Lp3_arrive_join
	buffer_wbl2 sc1
	s_waitcnt vmcnt(0)
	v_mov_b32_e32 v4, 0x400
	global_atomic_add v4, v5, s[12:13]

.LBB0_393:
	s_cmp_gt_i32 s97, 4
	s_cselect_b64 s[0:1], -1, 0
	s_and_b64 s[4:5], s[8:9], s[0:1]
	v_readlane_b32 s72, v254, 22
	s_andn2_b64 vcc, exec, s[4:5]
	v_readlane_b32 s82, v254, 32
	v_readlane_b32 s83, v254, 33
	v_readlane_b32 s86, v254, 36
	v_readlane_b32 s87, v254, 37
	v_readlane_b32 s73, v254, 23
	v_readlane_b32 s74, v254, 24
	v_readlane_b32 s75, v254, 25
	v_readlane_b32 s76, v254, 26
	v_readlane_b32 s77, v254, 27
	v_readlane_b32 s78, v254, 28
	v_readlane_b32 s79, v254, 29
	v_readlane_b32 s80, v254, 30
	v_readlane_b32 s81, v254, 31
	v_readlane_b32 s84, v254, 34
	v_readlane_b32 s85, v254, 35
	s_cbranch_vccnz .LBB0_447
	s_waitcnt vmcnt(0) lgkmcnt(0)
	s_barrier
	s_mov_b64 s[4:5], exec
	v_readlane_b32 s6, v254, 2
	v_readlane_b32 s7, v254, 3
	s_nop 1
	s_and_b64 s[6:7], s[4:5], s[6:7]
	s_mov_b64 exec, s[6:7]
	s_cbranch_execz .Lp3_wait_join
	v_mov_b32_e32 v1, 0x23fc0
	ds_read_b64 v[16:17], v1
	s_add_u32 s10, s62, 0x40e000
	s_addc_u32 s11, s63, 0
	v_mov_b32_e32 v1, 0x400
	s_mov_b32 s8, 0
.Lp3_spin:
	global_load_dword v2, v1, s[10:11] sc1
	s_waitcnt vmcnt(0) lgkmcnt(0)
	v_cmp_ge_u32_e32 vcc, v2, v17
	s_cbranch_vccnz .Lp3_spin_done
	s_sleep 1
	s_add_u32 s8, s8, 1
	s_cmp_lt_u32 s8, 0x100000
	s_cbranch_scc1 .Lp3_spin
